# GEMM K-loops: MFMA issue order within each 16-MFMA group changed to a snake over n so consecutive MFMAs share one operand register
# speedup vs baseline: 1.0069x; 1.0069x over previous
.LBB0_245:
	s_waitcnt lgkmcnt(0)
	s_barrier
	s_setprio 1
	s_waitcnt lgkmcnt(0)
	v_mfma_f32_16x16x32_bf16 v[82:85], v[166:169], v[190:193], v[82:85]
	v_mfma_f32_16x16x32_bf16 v[78:81], v[174:177], v[190:193], v[78:81]
	v_mfma_f32_16x16x32_bf16 v[46:49], v[174:177], v[182:185], v[46:49]
	v_mfma_f32_16x16x32_bf16 v[50:53], v[166:169], v[182:185], v[50:53]
	v_mfma_f32_16x16x32_bf16 v[34:37], v[166:169], v[62:65], v[34:37]
	v_mfma_f32_16x16x32_bf16 v[30:33], v[174:177], v[62:65], v[30:33]
	v_mfma_f32_16x16x32_bf16 v[10:13], v[174:177], v[54:57], v[10:13]
	v_mfma_f32_16x16x32_bf16 v[18:21], v[166:169], v[54:57], v[18:21]
	v_mfma_f32_16x16x32_bf16 v[82:85], v[170:173], v[194:197], v[82:85]
	v_mfma_f32_16x16x32_bf16 v[78:81], v[178:181], v[194:197], v[78:81]
	v_mfma_f32_16x16x32_bf16 v[46:49], v[178:181], v[186:189], v[46:49]
	v_mfma_f32_16x16x32_bf16 v[50:53], v[170:173], v[186:189], v[50:53]
	v_mfma_f32_16x16x32_bf16 v[34:37], v[170:173], v[66:69], v[34:37]
	v_mfma_f32_16x16x32_bf16 v[30:33], v[178:181], v[66:69], v[30:33]
	v_mfma_f32_16x16x32_bf16 v[10:13], v[178:181], v[58:61], v[10:13]
	v_mfma_f32_16x16x32_bf16 v[18:21], v[170:173], v[58:61], v[18:21]
	s_setprio 0
	s_setprio 1
	v_mfma_f32_16x16x32_bf16 v[74:77], v[150:153], v[190:193], v[74:77]
	v_mfma_f32_16x16x32_bf16 v[70:73], v[158:161], v[190:193], v[70:73]
	v_mfma_f32_16x16x32_bf16 v[38:41], v[158:161], v[182:185], v[38:41]
	v_mfma_f32_16x16x32_bf16 v[42:45], v[150:153], v[182:185], v[42:45]
	v_mfma_f32_16x16x32_bf16 v[26:29], v[150:153], v[62:65], v[26:29]
	v_mfma_f32_16x16x32_bf16 v[22:25], v[158:161], v[62:65], v[22:25]
	v_mfma_f32_16x16x32_bf16 v[2:5], v[158:161], v[54:57], v[2:5]
	v_mfma_f32_16x16x32_bf16 v[6:9], v[150:153], v[54:57], v[6:9]
	v_mfma_f32_16x16x32_bf16 v[74:77], v[154:157], v[194:197], v[74:77]
	v_mfma_f32_16x16x32_bf16 v[70:73], v[162:165], v[194:197], v[70:73]
	v_mfma_f32_16x16x32_bf16 v[38:41], v[162:165], v[186:189], v[38:41]
	v_mfma_f32_16x16x32_bf16 v[42:45], v[154:157], v[186:189], v[42:45]
	v_mfma_f32_16x16x32_bf16 v[26:29], v[154:157], v[66:69], v[26:29]
	v_mfma_f32_16x16x32_bf16 v[22:25], v[162:165], v[66:69], v[22:25]
	v_mfma_f32_16x16x32_bf16 v[2:5], v[162:165], v[58:61], v[2:5]
	v_mfma_f32_16x16x32_bf16 v[6:9], v[154:157], v[58:61], v[6:9]
	s_setprio 0
	s_barrier
	s_add_i32 s65, s65, 2
	s_add_u32 s8, s8, 0x100
	s_addc_u32 s9, s9, 0
	s_add_u32 s33, s33, 0x100
	s_addc_u32 s64, s64, 0
	s_cmp_gt_u32 s65, 29
	s_cbranch_scc1 .LBB0_256

.LBB0_250:
	s_waitcnt lgkmcnt(0)
	s_barrier
	s_setprio 1
	s_waitcnt lgkmcnt(0)
	v_mfma_f32_16x16x32_bf16 v[82:85], v[166:169], v[190:193], v[82:85]
	v_mfma_f32_16x16x32_bf16 v[78:81], v[174:177], v[190:193], v[78:81]
	v_mfma_f32_16x16x32_bf16 v[46:49], v[174:177], v[182:185], v[46:49]
	v_mfma_f32_16x16x32_bf16 v[50:53], v[166:169], v[182:185], v[50:53]
	v_mfma_f32_16x16x32_bf16 v[34:37], v[166:169], v[142:145], v[34:37]
	v_mfma_f32_16x16x32_bf16 v[30:33], v[174:177], v[142:145], v[30:33]
	v_mfma_f32_16x16x32_bf16 v[10:13], v[174:177], v[126:129], v[10:13]
	v_mfma_f32_16x16x32_bf16 v[18:21], v[166:169], v[126:129], v[18:21]
	v_mfma_f32_16x16x32_bf16 v[82:85], v[170:173], v[194:197], v[82:85]
	v_mfma_f32_16x16x32_bf16 v[78:81], v[178:181], v[194:197], v[78:81]
	v_mfma_f32_16x16x32_bf16 v[46:49], v[178:181], v[186:189], v[46:49]
	v_mfma_f32_16x16x32_bf16 v[50:53], v[170:173], v[186:189], v[50:53]
	v_mfma_f32_16x16x32_bf16 v[34:37], v[170:173], v[146:149], v[34:37]
	v_mfma_f32_16x16x32_bf16 v[30:33], v[178:181], v[146:149], v[30:33]
	v_mfma_f32_16x16x32_bf16 v[10:13], v[178:181], v[130:133], v[10:13]
	v_mfma_f32_16x16x32_bf16 v[18:21], v[170:173], v[130:133], v[18:21]
	s_setprio 0
	s_setprio 1
	v_mfma_f32_16x16x32_bf16 v[74:77], v[150:153], v[190:193], v[74:77]
	v_mfma_f32_16x16x32_bf16 v[70:73], v[158:161], v[190:193], v[70:73]
	v_mfma_f32_16x16x32_bf16 v[38:41], v[158:161], v[182:185], v[38:41]
	v_mfma_f32_16x16x32_bf16 v[42:45], v[150:153], v[182:185], v[42:45]
	v_mfma_f32_16x16x32_bf16 v[26:29], v[150:153], v[142:145], v[26:29]
	v_mfma_f32_16x16x32_bf16 v[22:25], v[158:161], v[142:145], v[22:25]
	v_mfma_f32_16x16x32_bf16 v[2:5], v[158:161], v[126:129], v[2:5]
	v_mfma_f32_16x16x32_bf16 v[6:9], v[150:153], v[126:129], v[6:9]
	v_mfma_f32_16x16x32_bf16 v[74:77], v[154:157], v[194:197], v[74:77]
	v_mfma_f32_16x16x32_bf16 v[70:73], v[162:165], v[194:197], v[70:73]
	v_mfma_f32_16x16x32_bf16 v[38:41], v[162:165], v[186:189], v[38:41]
	v_mfma_f32_16x16x32_bf16 v[42:45], v[154:157], v[186:189], v[42:45]
	v_mfma_f32_16x16x32_bf16 v[26:29], v[154:157], v[146:149], v[26:29]
	v_mfma_f32_16x16x32_bf16 v[22:25], v[162:165], v[146:149], v[22:25]
	v_mfma_f32_16x16x32_bf16 v[2:5], v[162:165], v[130:133], v[2:5]
	v_mfma_f32_16x16x32_bf16 v[6:9], v[154:157], v[130:133], v[6:9]
	s_setprio 0
	s_barrier
	v_add_u32_e32 v0, 0x18000, v235
	ds_read_b128 v[166:169], v0
	ds_read_b128 v[170:173], v0 offset:1024
	ds_read_b128 v[174:177], v0 offset:2048
	ds_read_b128 v[178:181], v0 offset:3072
	v_add_u32_e32 v0, 0x1c000, v235
	ds_read_b128 v[150:153], v0
	ds_read_b128 v[154:157], v0 offset:1024
	ds_read_b128 v[158:161], v0 offset:2048
	ds_read_b128 v[162:165], v0 offset:3072
	ds_read_b128 v[206:209], v245 offset:32768
	ds_read_b128 v[210:213], v245 offset:33792
	ds_read_b128 v[198:201], v245 offset:34816
	ds_read_b128 v[202:205], v245 offset:35840
	ds_read_b128 v[190:193], v245 offset:36864
	ds_read_b128 v[194:197], v245 offset:37888
	ds_read_b128 v[182:185], v245 offset:38912
	ds_read_b128 v[186:189], v245 offset:39936
	s_mov_b64 s[94:95], -1
	s_and_b64 vcc, exec, s[92:93]
	s_cbranch_vccz .LBB0_252
	s_waitcnt vmcnt(0)
	s_mov_b64 s[94:95], 0

.LBB0_1310:
	s_waitcnt lgkmcnt(0)
	s_barrier
	s_setprio 1
	s_waitcnt lgkmcnt(0)
	v_mfma_f32_16x16x32_bf16 v[78:81], v[150:153], v[190:193], v[78:81]
	v_mfma_f32_16x16x32_bf16 v[86:89], v[158:161], v[190:193], v[86:89]
	v_mfma_f32_16x16x32_bf16 v[114:117], v[158:161], v[182:185], v[114:117]
	v_mfma_f32_16x16x32_bf16 v[110:113], v[150:153], v[182:185], v[110:113]
	v_mfma_f32_16x16x32_bf16 v[130:133], v[150:153], v[174:177], v[130:133]
	v_mfma_f32_16x16x32_bf16 v[118:121], v[158:161], v[174:177], v[118:121]
	v_mfma_f32_16x16x32_bf16 v[82:85], v[158:161], v[166:169], v[82:85]
	v_mfma_f32_16x16x32_bf16 v[90:93], v[150:153], v[166:169], v[90:93]
	v_mfma_f32_16x16x32_bf16 v[78:81], v[154:157], v[194:197], v[78:81]
	v_mfma_f32_16x16x32_bf16 v[86:89], v[162:165], v[194:197], v[86:89]
	v_mfma_f32_16x16x32_bf16 v[114:117], v[162:165], v[186:189], v[114:117]
	v_mfma_f32_16x16x32_bf16 v[110:113], v[154:157], v[186:189], v[110:113]
	v_mfma_f32_16x16x32_bf16 v[130:133], v[154:157], v[178:181], v[130:133]
	v_mfma_f32_16x16x32_bf16 v[118:121], v[162:165], v[178:181], v[118:121]
	v_mfma_f32_16x16x32_bf16 v[82:85], v[162:165], v[170:173], v[82:85]
	v_mfma_f32_16x16x32_bf16 v[90:93], v[154:157], v[170:173], v[90:93]
	s_setprio 0
	s_setprio 1
	v_mfma_f32_16x16x32_bf16 v[94:97], v[134:137], v[190:193], v[94:97]
	v_mfma_f32_16x16x32_bf16 v[98:101], v[142:145], v[190:193], v[98:101]
	v_mfma_f32_16x16x32_bf16 v[126:129], v[142:145], v[182:185], v[126:129]
	v_mfma_f32_16x16x32_bf16 v[122:125], v[134:137], v[182:185], v[122:125]
	v_mfma_f32_16x16x32_bf16 v[106:109], v[134:137], v[174:177], v[106:109]
	v_mfma_f32_16x16x32_bf16 v[102:105], v[142:145], v[174:177], v[102:105]
	v_mfma_f32_16x16x32_bf16 v[62:65], v[142:145], v[166:169], v[62:65]
	v_mfma_f32_16x16x32_bf16 v[66:69], v[134:137], v[166:169], v[66:69]
	v_mfma_f32_16x16x32_bf16 v[94:97], v[138:141], v[194:197], v[94:97]
	v_mfma_f32_16x16x32_bf16 v[98:101], v[146:149], v[194:197], v[98:101]
	v_mfma_f32_16x16x32_bf16 v[126:129], v[146:149], v[186:189], v[126:129]
	v_mfma_f32_16x16x32_bf16 v[122:125], v[138:141], v[186:189], v[122:125]
	v_mfma_f32_16x16x32_bf16 v[106:109], v[138:141], v[178:181], v[106:109]
	v_mfma_f32_16x16x32_bf16 v[102:105], v[146:149], v[178:181], v[102:105]
	v_mfma_f32_16x16x32_bf16 v[62:65], v[146:149], v[170:173], v[62:65]
	v_mfma_f32_16x16x32_bf16 v[66:69], v[138:141], v[170:173], v[66:69]
	s_setprio 0
	s_barrier
	s_cmp_ge_u32 s60, s41
	s_cbranch_scc1 .LBB0_1321
.LBB0_1311:
	s_cmp_eq_u32 s60, s74
	s_cselect_b64 s[10:11], -1, 0
	s_or_b32 s14, s60, 1
	s_add_i32 s60, s60, 2
	s_mov_b32 s61, s15
	s_lshl_b64 s[62:63], s[60:61], 7
	v_add_u32_e32 v0, 0x10000, v235
	s_add_u32 s61, s56, s62
	ds_read_b128 v[150:153], v0
	ds_read_b128 v[154:157], v0 offset:1024
	ds_read_b128 v[158:161], v0 offset:2048
	ds_read_b128 v[162:165], v0 offset:3072
	v_add_u32_e32 v0, 0x14000, v235
	s_addc_u32 s66, s57, s63
	ds_read_b128 v[134:137], v0
	ds_read_b128 v[138:141], v0 offset:1024
	ds_read_b128 v[142:145], v0 offset:2048
	ds_read_b128 v[146:149], v0 offset:3072
	s_and_b64 s[64:65], s[10:11], exec
	s_cselect_b32 s62, 0, s62
	s_cselect_b32 s63, 0, s63
	s_add_u32 s62, s42, s62
	s_addc_u32 s63, s43, s63
	s_and_b64 s[64:65], s[10:11], exec
	s_cselect_b32 s65, s53, s66
	s_cselect_b32 s64, s52, s61
	s_lshl_b64 s[66:67], s[14:15], 7
	s_add_u32 s66, s33, s66
	s_addc_u32 s67, s84, s67
	v_lshl_add_u64 v[224:225], s[66:67], 0, v[202:203]
	s_add_i32 m0, s21, 0xc000
	ds_read_b128 v[166:169], v236
	ds_read_b128 v[170:173], v236 offset:1024
	ds_read_b128 v[174:177], v236 offset:2048
	ds_read_b128 v[178:181], v236 offset:3072
	ds_read_b128 v[182:185], v236 offset:4096
	ds_read_b128 v[186:189], v236 offset:5120
	ds_read_b128 v[190:193], v236 offset:6144
	ds_read_b128 v[194:197], v236 offset:7168
	global_load_lds_dwordx4 v[224:225], off
	v_lshl_add_u64 v[224:225], s[66:67], 0, v[198:199]
	s_add_i32 m0, s21, 0xe000
	s_nop 0
	global_load_lds_dwordx4 v[224:225], off
	s_waitcnt vmcnt(8)
	s_waitcnt lgkmcnt(0)
	s_barrier
	s_setprio 1
	s_waitcnt lgkmcnt(0)
	v_mfma_f32_16x16x32_bf16 v[30:33], v[150:153], v[166:169], v[30:33]
	v_mfma_f32_16x16x32_bf16 v[34:37], v[158:161], v[166:169], v[34:37]
	v_mfma_f32_16x16x32_bf16 v[2:5], v[158:161], v[174:177], v[2:5]
	v_mfma_f32_16x16x32_bf16 v[6:9], v[150:153], v[174:177], v[6:9]
	v_mfma_f32_16x16x32_bf16 v[22:25], v[150:153], v[182:185], v[22:25]
	v_mfma_f32_16x16x32_bf16 v[26:29], v[158:161], v[182:185], v[26:29]
	v_mfma_f32_16x16x32_bf16 v[58:61], v[158:161], v[190:193], v[58:61]
	v_mfma_f32_16x16x32_bf16 v[54:57], v[150:153], v[190:193], v[54:57]
	v_mfma_f32_16x16x32_bf16 v[30:33], v[154:157], v[170:173], v[30:33]
	v_mfma_f32_16x16x32_bf16 v[34:37], v[162:165], v[170:173], v[34:37]
	v_mfma_f32_16x16x32_bf16 v[2:5], v[162:165], v[178:181], v[2:5]
	v_mfma_f32_16x16x32_bf16 v[6:9], v[154:157], v[178:181], v[6:9]
	v_mfma_f32_16x16x32_bf16 v[22:25], v[154:157], v[186:189], v[22:25]
	v_mfma_f32_16x16x32_bf16 v[26:29], v[162:165], v[186:189], v[26:29]
	v_mfma_f32_16x16x32_bf16 v[58:61], v[162:165], v[194:197], v[58:61]
	v_mfma_f32_16x16x32_bf16 v[54:57], v[154:157], v[194:197], v[54:57]
	s_setprio 0
	s_setprio 1
	v_mfma_f32_16x16x32_bf16 v[46:49], v[134:137], v[166:169], v[46:49]
	v_mfma_f32_16x16x32_bf16 v[50:53], v[142:145], v[166:169], v[50:53]
	v_mfma_f32_16x16x32_bf16 v[18:21], v[142:145], v[174:177], v[18:21]
	v_mfma_f32_16x16x32_bf16 v[10:13], v[134:137], v[174:177], v[10:13]
	v_mfma_f32_16x16x32_bf16 v[38:41], v[134:137], v[182:185], v[38:41]
	v_mfma_f32_16x16x32_bf16 v[42:45], v[142:145], v[182:185], v[42:45]
	v_mfma_f32_16x16x32_bf16 v[74:77], v[142:145], v[190:193], v[74:77]
	v_mfma_f32_16x16x32_bf16 v[70:73], v[134:137], v[190:193], v[70:73]
	v_mfma_f32_16x16x32_bf16 v[46:49], v[138:141], v[170:173], v[46:49]
	v_mfma_f32_16x16x32_bf16 v[50:53], v[146:149], v[170:173], v[50:53]
	v_mfma_f32_16x16x32_bf16 v[18:21], v[146:149], v[178:181], v[18:21]
	v_mfma_f32_16x16x32_bf16 v[10:13], v[138:141], v[178:181], v[10:13]
	v_mfma_f32_16x16x32_bf16 v[38:41], v[138:141], v[186:189], v[38:41]
	v_mfma_f32_16x16x32_bf16 v[42:45], v[146:149], v[186:189], v[42:45]
	v_mfma_f32_16x16x32_bf16 v[74:77], v[146:149], v[194:197], v[74:77]
	v_mfma_f32_16x16x32_bf16 v[70:73], v[138:141], v[194:197], v[70:73]
	s_setprio 0
	s_barrier
	ds_read_b128 v[190:193], v236 offset:16384
	ds_read_b128 v[194:197], v236 offset:17408
	ds_read_b128 v[182:185], v236 offset:18432
	ds_read_b128 v[186:189], v236 offset:19456
	ds_read_b128 v[174:177], v236 offset:20480
	ds_read_b128 v[178:181], v236 offset:21504
	ds_read_b128 v[166:169], v236 offset:22528
	ds_read_b128 v[170:173], v236 offset:23552
	s_and_b64 s[10:11], s[58:59], s[10:11]
	s_mov_b64 s[66:67], -1
	s_and_b64 vcc, exec, s[10:11]
	v_lshl_add_u64 v[230:231], s[62:63], 0, v[200:201]
	v_lshl_add_u64 v[228:229], s[62:63], 0, v[14:15]
	v_lshl_add_u64 v[226:227], s[64:65], 0, v[202:203]
	v_lshl_add_u64 v[224:225], s[64:65], 0, v[198:199]
	s_cbranch_vccnz .LBB0_1313
	s_mov_b32 m0, s22
	s_add_u32 s66, s62, s0
	global_load_lds_dwordx4 v[230:231], off
	s_mov_b32 m0, s23
	s_addc_u32 s67, s63, 0
	global_load_lds_dwordx4 v[228:229], off
	v_lshl_add_u64 v[240:241], s[66:67], 0, v[200:201]
	s_mov_b32 m0, s25
	s_nop 0
	global_load_lds_dwordx4 v[240:241], off
	v_lshl_add_u64 v[240:241], s[66:67], 0, v[14:15]
	s_mov_b32 m0, s28
	s_mov_b64 s[66:67], 0
	global_load_lds_dwordx4 v[240:241], off
	s_mov_b32 m0, s21
	s_nop 0
	global_load_lds_dwordx4 v[226:227], off
	s_mov_b32 m0, s29
	s_nop 0
	global_load_lds_dwordx4 v[224:225], off
	s_waitcnt vmcnt(8)

.LBB0_1315:
	s_waitcnt lgkmcnt(0)
	s_xor_b64 s[66:67], s[10:11], -1
	s_barrier
	s_setprio 1
	s_waitcnt lgkmcnt(0)
	v_mfma_f32_16x16x32_bf16 v[78:81], v[150:153], v[190:193], v[78:81]
	v_mfma_f32_16x16x32_bf16 v[86:89], v[158:161], v[190:193], v[86:89]
	v_mfma_f32_16x16x32_bf16 v[114:117], v[158:161], v[182:185], v[114:117]
	v_mfma_f32_16x16x32_bf16 v[110:113], v[150:153], v[182:185], v[110:113]
	v_mfma_f32_16x16x32_bf16 v[130:133], v[150:153], v[174:177], v[130:133]
	v_mfma_f32_16x16x32_bf16 v[118:121], v[158:161], v[174:177], v[118:121]
	v_mfma_f32_16x16x32_bf16 v[82:85], v[158:161], v[166:169], v[82:85]
	v_mfma_f32_16x16x32_bf16 v[90:93], v[150:153], v[166:169], v[90:93]
	v_mfma_f32_16x16x32_bf16 v[78:81], v[154:157], v[194:197], v[78:81]
	v_mfma_f32_16x16x32_bf16 v[86:89], v[162:165], v[194:197], v[86:89]
	v_mfma_f32_16x16x32_bf16 v[114:117], v[162:165], v[186:189], v[114:117]
	v_mfma_f32_16x16x32_bf16 v[110:113], v[154:157], v[186:189], v[110:113]
	v_mfma_f32_16x16x32_bf16 v[130:133], v[154:157], v[178:181], v[130:133]
	v_mfma_f32_16x16x32_bf16 v[118:121], v[162:165], v[178:181], v[118:121]
	v_mfma_f32_16x16x32_bf16 v[82:85], v[162:165], v[170:173], v[82:85]
	v_mfma_f32_16x16x32_bf16 v[90:93], v[154:157], v[170:173], v[90:93]
	s_setprio 0
	s_setprio 1
	v_mfma_f32_16x16x32_bf16 v[94:97], v[134:137], v[190:193], v[94:97]
	v_mfma_f32_16x16x32_bf16 v[98:101], v[142:145], v[190:193], v[98:101]
	v_mfma_f32_16x16x32_bf16 v[126:129], v[142:145], v[182:185], v[126:129]
	v_mfma_f32_16x16x32_bf16 v[122:125], v[134:137], v[182:185], v[122:125]
	v_mfma_f32_16x16x32_bf16 v[106:109], v[134:137], v[174:177], v[106:109]
	v_mfma_f32_16x16x32_bf16 v[102:105], v[142:145], v[174:177], v[102:105]
	v_mfma_f32_16x16x32_bf16 v[62:65], v[142:145], v[166:169], v[62:65]
	v_mfma_f32_16x16x32_bf16 v[66:69], v[134:137], v[166:169], v[66:69]
	v_mfma_f32_16x16x32_bf16 v[94:97], v[138:141], v[194:197], v[94:97]
	v_mfma_f32_16x16x32_bf16 v[98:101], v[146:149], v[194:197], v[98:101]
	v_mfma_f32_16x16x32_bf16 v[126:129], v[146:149], v[186:189], v[126:129]
	v_mfma_f32_16x16x32_bf16 v[122:125], v[138:141], v[186:189], v[122:125]
	v_mfma_f32_16x16x32_bf16 v[106:109], v[138:141], v[178:181], v[106:109]
	v_mfma_f32_16x16x32_bf16 v[102:105], v[146:149], v[178:181], v[102:105]
	v_mfma_f32_16x16x32_bf16 v[62:65], v[146:149], v[170:173], v[62:65]
	v_mfma_f32_16x16x32_bf16 v[66:69], v[138:141], v[170:173], v[66:69]
	s_setprio 0
	s_barrier
	v_add_u32_e32 v0, 0x18000, v235
	ds_read_b128 v[150:153], v0
	ds_read_b128 v[154:157], v0 offset:1024
	ds_read_b128 v[158:161], v0 offset:2048
	ds_read_b128 v[162:165], v0 offset:3072
	v_add_u32_e32 v0, 0x1c000, v235
	ds_read_b128 v[134:137], v0
	ds_read_b128 v[138:141], v0 offset:1024
	ds_read_b128 v[142:145], v0 offset:2048
	ds_read_b128 v[146:149], v0 offset:3072
	ds_read_b128 v[190:193], v236 offset:32768
	ds_read_b128 v[194:197], v236 offset:33792
	ds_read_b128 v[182:185], v236 offset:34816
	ds_read_b128 v[186:189], v236 offset:35840
	ds_read_b128 v[174:177], v236 offset:36864
	ds_read_b128 v[178:181], v236 offset:37888
	ds_read_b128 v[166:169], v236 offset:38912
	ds_read_b128 v[170:173], v236 offset:39936
	v_cndmask_b32_e64 v0, 0, 1, s[66:67]
	v_cmp_ne_u32_e64 s[10:11], 1, v0
	s_andn2_b64 vcc, exec, s[66:67]
	s_mov_b64 s[66:67], -1
	s_cbranch_vccnz .LBB0_1317
	s_add_u32 s64, s64, s0
	s_addc_u32 s65, s65, 0
	s_mov_b32 m0, s36
	v_lshl_add_u64 v[240:241], s[64:65], 0, v[202:203]
	global_load_lds_dwordx4 v[240:241], off
	v_lshl_add_u64 v[240:241], s[64:65], 0, v[198:199]
	s_mov_b32 m0, s38
	s_mov_b64 s[66:67], 0
	global_load_lds_dwordx4 v[240:241], off
	s_waitcnt vmcnt(8)

.LBB0_1319:
	s_waitcnt lgkmcnt(0)
	s_barrier
	s_setprio 1
	s_waitcnt lgkmcnt(0)
	v_mfma_f32_16x16x32_bf16 v[30:33], v[150:153], v[190:193], v[30:33]
	v_mfma_f32_16x16x32_bf16 v[34:37], v[158:161], v[190:193], v[34:37]
	v_mfma_f32_16x16x32_bf16 v[2:5], v[158:161], v[182:185], v[2:5]
	v_mfma_f32_16x16x32_bf16 v[6:9], v[150:153], v[182:185], v[6:9]
	v_mfma_f32_16x16x32_bf16 v[22:25], v[150:153], v[174:177], v[22:25]
	v_mfma_f32_16x16x32_bf16 v[26:29], v[158:161], v[174:177], v[26:29]
	v_mfma_f32_16x16x32_bf16 v[58:61], v[158:161], v[166:169], v[58:61]
	v_mfma_f32_16x16x32_bf16 v[54:57], v[150:153], v[166:169], v[54:57]
	v_mfma_f32_16x16x32_bf16 v[30:33], v[154:157], v[194:197], v[30:33]
	v_mfma_f32_16x16x32_bf16 v[34:37], v[162:165], v[194:197], v[34:37]
	v_mfma_f32_16x16x32_bf16 v[2:5], v[162:165], v[186:189], v[2:5]
	v_mfma_f32_16x16x32_bf16 v[6:9], v[154:157], v[186:189], v[6:9]
	v_mfma_f32_16x16x32_bf16 v[22:25], v[154:157], v[178:181], v[22:25]
	v_mfma_f32_16x16x32_bf16 v[26:29], v[162:165], v[178:181], v[26:29]
	v_mfma_f32_16x16x32_bf16 v[58:61], v[162:165], v[170:173], v[58:61]
	v_mfma_f32_16x16x32_bf16 v[54:57], v[154:157], v[170:173], v[54:57]
	s_setprio 0
	s_setprio 1
	v_mfma_f32_16x16x32_bf16 v[46:49], v[134:137], v[190:193], v[46:49]
	v_mfma_f32_16x16x32_bf16 v[50:53], v[142:145], v[190:193], v[50:53]
	v_mfma_f32_16x16x32_bf16 v[18:21], v[142:145], v[182:185], v[18:21]
	v_mfma_f32_16x16x32_bf16 v[10:13], v[134:137], v[182:185], v[10:13]
	v_mfma_f32_16x16x32_bf16 v[38:41], v[134:137], v[174:177], v[38:41]
	v_mfma_f32_16x16x32_bf16 v[42:45], v[142:145], v[174:177], v[42:45]
	v_mfma_f32_16x16x32_bf16 v[74:77], v[142:145], v[166:169], v[74:77]
	v_mfma_f32_16x16x32_bf16 v[70:73], v[134:137], v[166:169], v[70:73]
	v_mfma_f32_16x16x32_bf16 v[46:49], v[138:141], v[194:197], v[46:49]
	v_mfma_f32_16x16x32_bf16 v[50:53], v[146:149], v[194:197], v[50:53]
	v_mfma_f32_16x16x32_bf16 v[18:21], v[146:149], v[186:189], v[18:21]
	v_mfma_f32_16x16x32_bf16 v[10:13], v[138:141], v[186:189], v[10:13]
	v_mfma_f32_16x16x32_bf16 v[38:41], v[138:141], v[178:181], v[38:41]
	v_mfma_f32_16x16x32_bf16 v[42:45], v[146:149], v[178:181], v[42:45]
	v_mfma_f32_16x16x32_bf16 v[74:77], v[146:149], v[170:173], v[74:77]
	v_mfma_f32_16x16x32_bf16 v[70:73], v[138:141], v[170:173], v[70:73]
	s_setprio 0
	s_barrier
	ds_read_b128 v[190:193], v236 offset:49152
	ds_read_b128 v[194:197], v236 offset:50176
	ds_read_b128 v[182:185], v236 offset:51200
	ds_read_b128 v[186:189], v236 offset:52224
	ds_read_b128 v[174:177], v236 offset:53248
	ds_read_b128 v[178:181], v236 offset:54272
	ds_read_b128 v[166:169], v236 offset:55296
	ds_read_b128 v[170:173], v236 offset:56320
	s_and_b64 vcc, exec, s[10:11]
	s_cbranch_vccnz .LBB0_1310
	s_mov_b32 m0, s68
	v_lshl_add_u64 v[230:231], v[230:231], 0, s[16:17]
	s_add_u32 s10, s62, s0
	global_load_lds_dwordx4 v[230:231], off
	v_lshl_add_u64 v[228:229], v[228:229], 0, s[16:17]
	s_mov_b32 m0, s69
	s_addc_u32 s11, s63, 0
	global_load_lds_dwordx4 v[228:229], off
	v_lshl_add_u64 v[228:229], s[10:11], 0, v[200:201]
	v_lshl_add_u64 v[228:229], v[228:229], 0, s[16:17]
	s_mov_b32 m0, s72
	v_lshl_add_u64 v[226:227], v[226:227], 0, s[16:17]
	global_load_lds_dwordx4 v[228:229], off
	v_lshl_add_u64 v[228:229], s[10:11], 0, v[14:15]
	v_lshl_add_u64 v[228:229], v[228:229], 0, s[16:17]
	s_mov_b32 m0, s73
	v_lshl_add_u64 v[224:225], v[224:225], 0, s[16:17]
	global_load_lds_dwordx4 v[228:229], off
	s_mov_b32 m0, s70
	s_nop 0
	global_load_lds_dwordx4 v[226:227], off
	s_mov_b32 m0, s71
	s_nop 0
	global_load_lds_dwordx4 v[224:225], off
	s_waitcnt vmcnt(8)
	s_branch .LBB0_1310

.LBB0_1532:
	s_waitcnt lgkmcnt(0)
	s_barrier
	s_setprio 1
	s_waitcnt lgkmcnt(0)
	v_mfma_f32_16x16x32_bf16 v[66:69], v[150:153], v[190:193], v[66:69]
	v_mfma_f32_16x16x32_bf16 v[62:65], v[158:161], v[190:193], v[62:65]
	v_mfma_f32_16x16x32_bf16 v[46:49], v[158:161], v[182:185], v[46:49]
	v_mfma_f32_16x16x32_bf16 v[50:53], v[150:153], v[182:185], v[50:53]
	v_mfma_f32_16x16x32_bf16 v[34:37], v[150:153], v[174:177], v[34:37]
	v_mfma_f32_16x16x32_bf16 v[30:33], v[158:161], v[174:177], v[30:33]
	v_mfma_f32_16x16x32_bf16 v[10:13], v[158:161], v[166:169], v[10:13]
	v_mfma_f32_16x16x32_bf16 v[18:21], v[150:153], v[166:169], v[18:21]
	v_mfma_f32_16x16x32_bf16 v[66:69], v[154:157], v[194:197], v[66:69]
	v_mfma_f32_16x16x32_bf16 v[62:65], v[162:165], v[194:197], v[62:65]
	v_mfma_f32_16x16x32_bf16 v[46:49], v[162:165], v[186:189], v[46:49]
	v_mfma_f32_16x16x32_bf16 v[50:53], v[154:157], v[186:189], v[50:53]
	v_mfma_f32_16x16x32_bf16 v[34:37], v[154:157], v[178:181], v[34:37]
	v_mfma_f32_16x16x32_bf16 v[30:33], v[162:165], v[178:181], v[30:33]
	v_mfma_f32_16x16x32_bf16 v[10:13], v[162:165], v[170:173], v[10:13]
	v_mfma_f32_16x16x32_bf16 v[18:21], v[154:157], v[170:173], v[18:21]
	s_setprio 0
	s_setprio 1
	v_mfma_f32_16x16x32_bf16 v[58:61], v[134:137], v[190:193], v[58:61]
	v_mfma_f32_16x16x32_bf16 v[54:57], v[142:145], v[190:193], v[54:57]
	v_mfma_f32_16x16x32_bf16 v[38:41], v[142:145], v[182:185], v[38:41]
	v_mfma_f32_16x16x32_bf16 v[42:45], v[134:137], v[182:185], v[42:45]
	v_mfma_f32_16x16x32_bf16 v[26:29], v[134:137], v[174:177], v[26:29]
	v_mfma_f32_16x16x32_bf16 v[22:25], v[142:145], v[174:177], v[22:25]
	v_mfma_f32_16x16x32_bf16 v[2:5], v[142:145], v[166:169], v[2:5]
	v_mfma_f32_16x16x32_bf16 v[6:9], v[134:137], v[166:169], v[6:9]
	v_mfma_f32_16x16x32_bf16 v[58:61], v[138:141], v[194:197], v[58:61]
	v_mfma_f32_16x16x32_bf16 v[54:57], v[146:149], v[194:197], v[54:57]
	v_mfma_f32_16x16x32_bf16 v[38:41], v[146:149], v[186:189], v[38:41]
	v_mfma_f32_16x16x32_bf16 v[42:45], v[138:141], v[186:189], v[42:45]
	v_mfma_f32_16x16x32_bf16 v[26:29], v[138:141], v[178:181], v[26:29]
	v_mfma_f32_16x16x32_bf16 v[22:25], v[146:149], v[178:181], v[22:25]
	v_mfma_f32_16x16x32_bf16 v[2:5], v[146:149], v[170:173], v[2:5]
	v_mfma_f32_16x16x32_bf16 v[6:9], v[138:141], v[170:173], v[6:9]
	s_setprio 0
	s_barrier
	s_add_i32 s33, s33, 2
	s_add_u32 s48, s48, 0x100
	s_addc_u32 s49, s49, 0
	s_add_u32 s70, s70, 0x100
	s_addc_u32 s71, s71, 0
	s_cmp_gt_u32 s33, 29
	s_cbranch_scc1 .LBB0_1543
.LBB0_1533:
	v_add_u32_e32 v134, 0x10000, v218
	v_add_u32_e32 v146, 0x14000, v218
	ds_read_b128 v[150:153], v134
	ds_read_b128 v[154:157], v134 offset:1024
	ds_read_b128 v[158:161], v134 offset:2048
	ds_read_b128 v[162:165], v134 offset:3072
	ds_read_b128 v[134:137], v146
	ds_read_b128 v[138:141], v146 offset:1024
	ds_read_b128 v[142:145], v146 offset:2048
	ds_read_b128 v[146:149], v146 offset:3072
	s_add_u32 s52, s48, 0xfff80080
	s_addc_u32 s53, s49, -1
	s_cmp_lg_u32 s33, 28
	s_cselect_b64 s[54:55], -1, 0
	s_and_b64 s[50:51], s[54:55], exec
	s_cselect_b32 s51, s71, s11
	s_cselect_b32 s50, s70, s69
	s_cselect_b32 s53, s53, s13
	s_cselect_b32 s52, s52, s68
	v_lshl_add_u64 v[208:209], s[48:49], 0, v[204:205]
	s_add_i32 m0, s22, 0xc000
	ds_read_b128 v[166:169], v219
	ds_read_b128 v[170:173], v219 offset:1024
	ds_read_b128 v[174:177], v219 offset:2048
	ds_read_b128 v[178:181], v219 offset:3072
	ds_read_b128 v[182:185], v219 offset:4096
	ds_read_b128 v[186:189], v219 offset:5120
	ds_read_b128 v[190:193], v219 offset:6144
	ds_read_b128 v[194:197], v219 offset:7168
	global_load_lds_dwordx4 v[208:209], off
	v_lshl_add_u64 v[208:209], s[48:49], 0, v[206:207]
	s_add_i32 m0, s22, 0xe000
	s_nop 0
	global_load_lds_dwordx4 v[208:209], off
	s_waitcnt vmcnt(8)
	s_waitcnt lgkmcnt(0)
	s_barrier
	s_setprio 1
	s_waitcnt lgkmcnt(0)
	v_mfma_f32_16x16x32_bf16 v[130:133], v[150:153], v[166:169], v[130:133]
	v_mfma_f32_16x16x32_bf16 v[126:129], v[158:161], v[166:169], v[126:129]
	v_mfma_f32_16x16x32_bf16 v[110:113], v[158:161], v[174:177], v[110:113]
	v_mfma_f32_16x16x32_bf16 v[114:117], v[150:153], v[174:177], v[114:117]
	v_mfma_f32_16x16x32_bf16 v[98:101], v[150:153], v[182:185], v[98:101]
	v_mfma_f32_16x16x32_bf16 v[94:97], v[158:161], v[182:185], v[94:97]
	v_mfma_f32_16x16x32_bf16 v[78:81], v[158:161], v[190:193], v[78:81]
	v_mfma_f32_16x16x32_bf16 v[82:85], v[150:153], v[190:193], v[82:85]
	v_mfma_f32_16x16x32_bf16 v[130:133], v[154:157], v[170:173], v[130:133]
	v_mfma_f32_16x16x32_bf16 v[126:129], v[162:165], v[170:173], v[126:129]
	v_mfma_f32_16x16x32_bf16 v[110:113], v[162:165], v[178:181], v[110:113]
	v_mfma_f32_16x16x32_bf16 v[114:117], v[154:157], v[178:181], v[114:117]
	v_mfma_f32_16x16x32_bf16 v[98:101], v[154:157], v[186:189], v[98:101]
	v_mfma_f32_16x16x32_bf16 v[94:97], v[162:165], v[186:189], v[94:97]
	v_mfma_f32_16x16x32_bf16 v[78:81], v[162:165], v[194:197], v[78:81]
	v_mfma_f32_16x16x32_bf16 v[82:85], v[154:157], v[194:197], v[82:85]
	s_setprio 0
	s_setprio 1
	v_mfma_f32_16x16x32_bf16 v[122:125], v[134:137], v[166:169], v[122:125]
	v_mfma_f32_16x16x32_bf16 v[118:121], v[142:145], v[166:169], v[118:121]
	v_mfma_f32_16x16x32_bf16 v[102:105], v[142:145], v[174:177], v[102:105]
	v_mfma_f32_16x16x32_bf16 v[106:109], v[134:137], v[174:177], v[106:109]
	v_mfma_f32_16x16x32_bf16 v[90:93], v[134:137], v[182:185], v[90:93]
	v_mfma_f32_16x16x32_bf16 v[86:89], v[142:145], v[182:185], v[86:89]
	v_mfma_f32_16x16x32_bf16 v[70:73], v[142:145], v[190:193], v[70:73]
	v_mfma_f32_16x16x32_bf16 v[74:77], v[134:137], v[190:193], v[74:77]
	v_mfma_f32_16x16x32_bf16 v[122:125], v[138:141], v[170:173], v[122:125]
	v_mfma_f32_16x16x32_bf16 v[118:121], v[146:149], v[170:173], v[118:121]
	v_mfma_f32_16x16x32_bf16 v[102:105], v[146:149], v[178:181], v[102:105]
	v_mfma_f32_16x16x32_bf16 v[106:109], v[138:141], v[178:181], v[106:109]
	v_mfma_f32_16x16x32_bf16 v[90:93], v[138:141], v[186:189], v[90:93]
	v_mfma_f32_16x16x32_bf16 v[86:89], v[146:149], v[186:189], v[86:89]
	v_mfma_f32_16x16x32_bf16 v[70:73], v[146:149], v[194:197], v[70:73]
	v_mfma_f32_16x16x32_bf16 v[74:77], v[138:141], v[194:197], v[74:77]
	s_setprio 0
	s_barrier
	ds_read_b128 v[190:193], v219 offset:16384
	ds_read_b128 v[194:197], v219 offset:17408
	ds_read_b128 v[182:185], v219 offset:18432
	ds_read_b128 v[186:189], v219 offset:19456
	ds_read_b128 v[174:177], v219 offset:20480
	ds_read_b128 v[178:181], v219 offset:21504
	ds_read_b128 v[166:169], v219 offset:22528
	ds_read_b128 v[170:173], v219 offset:23552
	s_or_b64 s[54:55], s[40:41], s[54:55]
	s_xor_b64 s[56:57], s[54:55], -1
	s_mov_b64 s[58:59], -1
	s_and_b64 vcc, exec, s[56:57]
	s_cbranch_vccz .LBB0_1535
	s_waitcnt vmcnt(2)
	s_mov_b64 s[58:59], 0

.LBB0_1537:
	s_waitcnt lgkmcnt(0)
	s_barrier
	s_setprio 1
	s_waitcnt lgkmcnt(0)
	v_mfma_f32_16x16x32_bf16 v[66:69], v[150:153], v[190:193], v[66:69]
	v_mfma_f32_16x16x32_bf16 v[62:65], v[158:161], v[190:193], v[62:65]
	v_mfma_f32_16x16x32_bf16 v[46:49], v[158:161], v[182:185], v[46:49]
	v_mfma_f32_16x16x32_bf16 v[50:53], v[150:153], v[182:185], v[50:53]
	v_mfma_f32_16x16x32_bf16 v[34:37], v[150:153], v[174:177], v[34:37]
	v_mfma_f32_16x16x32_bf16 v[30:33], v[158:161], v[174:177], v[30:33]
	v_mfma_f32_16x16x32_bf16 v[10:13], v[158:161], v[166:169], v[10:13]
	v_mfma_f32_16x16x32_bf16 v[18:21], v[150:153], v[166:169], v[18:21]
	v_mfma_f32_16x16x32_bf16 v[66:69], v[154:157], v[194:197], v[66:69]
	v_mfma_f32_16x16x32_bf16 v[62:65], v[162:165], v[194:197], v[62:65]
	v_mfma_f32_16x16x32_bf16 v[46:49], v[162:165], v[186:189], v[46:49]
	v_mfma_f32_16x16x32_bf16 v[50:53], v[154:157], v[186:189], v[50:53]
	v_mfma_f32_16x16x32_bf16 v[34:37], v[154:157], v[178:181], v[34:37]
	v_mfma_f32_16x16x32_bf16 v[30:33], v[162:165], v[178:181], v[30:33]
	v_mfma_f32_16x16x32_bf16 v[10:13], v[162:165], v[170:173], v[10:13]
	v_mfma_f32_16x16x32_bf16 v[18:21], v[154:157], v[170:173], v[18:21]
	s_setprio 0
	s_setprio 1
	v_mfma_f32_16x16x32_bf16 v[58:61], v[134:137], v[190:193], v[58:61]
	v_mfma_f32_16x16x32_bf16 v[54:57], v[142:145], v[190:193], v[54:57]
	v_mfma_f32_16x16x32_bf16 v[38:41], v[142:145], v[182:185], v[38:41]
	v_mfma_f32_16x16x32_bf16 v[42:45], v[134:137], v[182:185], v[42:45]
	v_mfma_f32_16x16x32_bf16 v[26:29], v[134:137], v[174:177], v[26:29]
	v_mfma_f32_16x16x32_bf16 v[22:25], v[142:145], v[174:177], v[22:25]
	v_mfma_f32_16x16x32_bf16 v[2:5], v[142:145], v[166:169], v[2:5]
	v_mfma_f32_16x16x32_bf16 v[6:9], v[134:137], v[166:169], v[6:9]
	v_mfma_f32_16x16x32_bf16 v[58:61], v[138:141], v[194:197], v[58:61]
	v_mfma_f32_16x16x32_bf16 v[54:57], v[146:149], v[194:197], v[54:57]
	v_mfma_f32_16x16x32_bf16 v[38:41], v[146:149], v[186:189], v[38:41]
	v_mfma_f32_16x16x32_bf16 v[42:45], v[138:141], v[186:189], v[42:45]
	v_mfma_f32_16x16x32_bf16 v[26:29], v[138:141], v[178:181], v[26:29]
	v_mfma_f32_16x16x32_bf16 v[22:25], v[146:149], v[178:181], v[22:25]
	v_mfma_f32_16x16x32_bf16 v[2:5], v[146:149], v[170:173], v[2:5]
	v_mfma_f32_16x16x32_bf16 v[6:9], v[138:141], v[170:173], v[6:9]
	s_setprio 0
	s_barrier
	v_add_u32_e32 v134, 0x18000, v218
	v_add_u32_e32 v146, 0x1c000, v218
	ds_read_b128 v[150:153], v134
	ds_read_b128 v[154:157], v134 offset:1024
	ds_read_b128 v[158:161], v134 offset:2048
	ds_read_b128 v[162:165], v134 offset:3072
	ds_read_b128 v[134:137], v146
	ds_read_b128 v[138:141], v146 offset:1024
	ds_read_b128 v[142:145], v146 offset:2048
	ds_read_b128 v[146:149], v146 offset:3072
	ds_read_b128 v[190:193], v219 offset:32768
	ds_read_b128 v[194:197], v219 offset:33792
	ds_read_b128 v[182:185], v219 offset:34816
	ds_read_b128 v[186:189], v219 offset:35840
	ds_read_b128 v[174:177], v219 offset:36864
	ds_read_b128 v[178:181], v219 offset:37888
	ds_read_b128 v[166:169], v219 offset:38912
	ds_read_b128 v[170:173], v219 offset:39936
	s_mov_b64 s[58:59], -1
	s_and_b64 vcc, exec, s[56:57]
	s_cbranch_vccz .LBB0_1539
	s_waitcnt vmcnt(0)
	s_mov_b64 s[58:59], 0

.LBB0_1541:
	s_waitcnt lgkmcnt(0)
	s_barrier
	s_setprio 1
	s_waitcnt lgkmcnt(0)
	v_mfma_f32_16x16x32_bf16 v[130:133], v[150:153], v[190:193], v[130:133]
	v_mfma_f32_16x16x32_bf16 v[126:129], v[158:161], v[190:193], v[126:129]
	v_mfma_f32_16x16x32_bf16 v[110:113], v[158:161], v[182:185], v[110:113]
	v_mfma_f32_16x16x32_bf16 v[114:117], v[150:153], v[182:185], v[114:117]
	v_mfma_f32_16x16x32_bf16 v[98:101], v[150:153], v[174:177], v[98:101]
	v_mfma_f32_16x16x32_bf16 v[94:97], v[158:161], v[174:177], v[94:97]
	v_mfma_f32_16x16x32_bf16 v[78:81], v[158:161], v[166:169], v[78:81]
	v_mfma_f32_16x16x32_bf16 v[82:85], v[150:153], v[166:169], v[82:85]
	v_mfma_f32_16x16x32_bf16 v[130:133], v[154:157], v[194:197], v[130:133]
	v_mfma_f32_16x16x32_bf16 v[126:129], v[162:165], v[194:197], v[126:129]
	v_mfma_f32_16x16x32_bf16 v[110:113], v[162:165], v[186:189], v[110:113]
	v_mfma_f32_16x16x32_bf16 v[114:117], v[154:157], v[186:189], v[114:117]
	v_mfma_f32_16x16x32_bf16 v[98:101], v[154:157], v[178:181], v[98:101]
	v_mfma_f32_16x16x32_bf16 v[94:97], v[162:165], v[178:181], v[94:97]
	v_mfma_f32_16x16x32_bf16 v[78:81], v[162:165], v[170:173], v[78:81]
	v_mfma_f32_16x16x32_bf16 v[82:85], v[154:157], v[170:173], v[82:85]
	s_setprio 0
	s_setprio 1
	v_mfma_f32_16x16x32_bf16 v[122:125], v[134:137], v[190:193], v[122:125]
	v_mfma_f32_16x16x32_bf16 v[118:121], v[142:145], v[190:193], v[118:121]
	v_mfma_f32_16x16x32_bf16 v[102:105], v[142:145], v[182:185], v[102:105]
	v_mfma_f32_16x16x32_bf16 v[106:109], v[134:137], v[182:185], v[106:109]
	v_mfma_f32_16x16x32_bf16 v[90:93], v[134:137], v[174:177], v[90:93]
	v_mfma_f32_16x16x32_bf16 v[86:89], v[142:145], v[174:177], v[86:89]
	v_mfma_f32_16x16x32_bf16 v[70:73], v[142:145], v[166:169], v[70:73]
	v_mfma_f32_16x16x32_bf16 v[74:77], v[134:137], v[166:169], v[74:77]
	v_mfma_f32_16x16x32_bf16 v[122:125], v[138:141], v[194:197], v[122:125]
	v_mfma_f32_16x16x32_bf16 v[118:121], v[146:149], v[194:197], v[118:121]
	v_mfma_f32_16x16x32_bf16 v[102:105], v[146:149], v[186:189], v[102:105]
	v_mfma_f32_16x16x32_bf16 v[106:109], v[138:141], v[186:189], v[106:109]
	v_mfma_f32_16x16x32_bf16 v[90:93], v[138:141], v[178:181], v[90:93]
	v_mfma_f32_16x16x32_bf16 v[86:89], v[146:149], v[178:181], v[86:89]
	v_mfma_f32_16x16x32_bf16 v[70:73], v[146:149], v[170:173], v[70:73]
	v_mfma_f32_16x16x32_bf16 v[74:77], v[138:141], v[170:173], v[74:77]
	s_setprio 0
	s_barrier
	ds_read_b128 v[190:193], v219 offset:49152
	ds_read_b128 v[194:197], v219 offset:50176
	ds_read_b128 v[182:185], v219 offset:51200
	ds_read_b128 v[186:189], v219 offset:52224
	ds_read_b128 v[174:177], v219 offset:53248
	ds_read_b128 v[178:181], v219 offset:54272
	ds_read_b128 v[166:169], v219 offset:55296
	ds_read_b128 v[170:173], v219 offset:56320
	s_andn2_b64 vcc, exec, s[54:55]
	s_cbranch_vccnz .LBB0_1532
	s_mov_b32 m0, s47
	v_lshl_add_u64 v[216:217], v[216:217], 0, s[16:17]
	s_add_u32 s50, s50, 0x80080
	global_load_lds_dwordx4 v[216:217], off
	v_lshl_add_u64 v[212:213], v[212:213], 0, s[16:17]
	s_mov_b32 m0, s60
	s_addc_u32 s51, s51, 0
	global_load_lds_dwordx4 v[212:213], off
	v_lshl_add_u64 v[212:213], s[50:51], 0, v[198:199]
	s_mov_b32 m0, s63
	v_lshl_add_u64 v[210:211], v[210:211], 0, s[16:17]
	global_load_lds_dwordx4 v[212:213], off
	v_lshl_add_u64 v[212:213], s[50:51], 0, v[202:203]
	s_mov_b32 m0, s64
	v_lshl_add_u64 v[208:209], v[208:209], 0, s[16:17]
	global_load_lds_dwordx4 v[212:213], off
	s_mov_b32 m0, s61
	s_nop 0
	global_load_lds_dwordx4 v[210:211], off
	s_mov_b32 m0, s62
	s_nop 0
	global_load_lds_dwordx4 v[208:209], off
	s_waitcnt vmcnt(8)
	s_branch .LBB0_1532

.LBB0_1632:
	s_waitcnt lgkmcnt(0)
	s_barrier
	s_setprio 1
	s_waitcnt lgkmcnt(0)
	v_mfma_f32_16x16x32_bf16 v[70:73], v[150:153], v[190:193], v[70:73]
	v_mfma_f32_16x16x32_bf16 v[74:77], v[158:161], v[190:193], v[74:77]
	v_mfma_f32_16x16x32_bf16 v[90:93], v[158:161], v[182:185], v[90:93]
	v_mfma_f32_16x16x32_bf16 v[86:89], v[150:153], v[182:185], v[86:89]
	v_mfma_f32_16x16x32_bf16 v[102:105], v[150:153], v[174:177], v[102:105]
	v_mfma_f32_16x16x32_bf16 v[106:109], v[158:161], v[174:177], v[106:109]
	v_mfma_f32_16x16x32_bf16 v[122:125], v[158:161], v[166:169], v[122:125]
	v_mfma_f32_16x16x32_bf16 v[118:121], v[150:153], v[166:169], v[118:121]
	v_mfma_f32_16x16x32_bf16 v[70:73], v[154:157], v[194:197], v[70:73]
	v_mfma_f32_16x16x32_bf16 v[74:77], v[162:165], v[194:197], v[74:77]
	v_mfma_f32_16x16x32_bf16 v[90:93], v[162:165], v[186:189], v[90:93]
	v_mfma_f32_16x16x32_bf16 v[86:89], v[154:157], v[186:189], v[86:89]
	v_mfma_f32_16x16x32_bf16 v[102:105], v[154:157], v[178:181], v[102:105]
	v_mfma_f32_16x16x32_bf16 v[106:109], v[162:165], v[178:181], v[106:109]
	v_mfma_f32_16x16x32_bf16 v[122:125], v[162:165], v[170:173], v[122:125]
	v_mfma_f32_16x16x32_bf16 v[118:121], v[154:157], v[170:173], v[118:121]
	s_setprio 0
	s_setprio 1
	v_mfma_f32_16x16x32_bf16 v[82:85], v[134:137], v[190:193], v[82:85]
	v_mfma_f32_16x16x32_bf16 v[78:81], v[142:145], v[190:193], v[78:81]
	v_mfma_f32_16x16x32_bf16 v[94:97], v[142:145], v[182:185], v[94:97]
	v_mfma_f32_16x16x32_bf16 v[98:101], v[134:137], v[182:185], v[98:101]
	v_mfma_f32_16x16x32_bf16 v[114:117], v[134:137], v[174:177], v[114:117]
	v_mfma_f32_16x16x32_bf16 v[110:113], v[142:145], v[174:177], v[110:113]
	v_mfma_f32_16x16x32_bf16 v[126:129], v[142:145], v[166:169], v[126:129]
	v_mfma_f32_16x16x32_bf16 v[130:133], v[134:137], v[166:169], v[130:133]
	v_mfma_f32_16x16x32_bf16 v[82:85], v[138:141], v[194:197], v[82:85]
	v_mfma_f32_16x16x32_bf16 v[78:81], v[146:149], v[194:197], v[78:81]
	v_mfma_f32_16x16x32_bf16 v[94:97], v[146:149], v[186:189], v[94:97]
	v_mfma_f32_16x16x32_bf16 v[98:101], v[138:141], v[186:189], v[98:101]
	v_mfma_f32_16x16x32_bf16 v[114:117], v[138:141], v[178:181], v[114:117]
	v_mfma_f32_16x16x32_bf16 v[110:113], v[146:149], v[178:181], v[110:113]
	v_mfma_f32_16x16x32_bf16 v[126:129], v[146:149], v[170:173], v[126:129]
	v_mfma_f32_16x16x32_bf16 v[130:133], v[138:141], v[170:173], v[130:133]
	s_setprio 0
	s_barrier
	s_add_i32 s25, s25, 2
	s_cmpk_gt_u32 s25, 0x7d
	s_cbranch_scc1 .LBB0_1643
.LBB0_1633:
	s_mov_b64 s[10:11], s[66:67]
	s_add_u32 s66, s10, 0x100
	s_addc_u32 s67, s11, 0
	v_add_u32_e32 v0, 0x10000, v250
	s_add_u32 s28, s14, s10
	ds_read_b128 v[150:153], v0
	ds_read_b128 v[154:157], v0 offset:1024
	ds_read_b128 v[158:161], v0 offset:2048
	ds_read_b128 v[162:165], v0 offset:3072
	v_add_u32_e32 v0, 0x14000, v250
	s_addc_u32 s33, s23, s11
	ds_read_b128 v[134:137], v0
	ds_read_b128 v[138:141], v0 offset:1024
	ds_read_b128 v[142:145], v0 offset:2048
	ds_read_b128 v[146:149], v0 offset:3072
	s_cmpk_eq_i32 s25, 0x7c
	s_cselect_b64 s[72:73], -1, 0
	s_and_b64 s[68:69], s[72:73], exec
	s_cselect_b32 s61, 0, s66
	s_cselect_b32 s38, 0, s67
	s_cselect_b32 s71, s0, s33
	s_cselect_b32 s70, s2, s28
	s_add_u32 s68, s48, s61
	s_addc_u32 s69, s49, s38
	v_lshl_add_u64 v[230:231], v[226:227], 0, s[10:11]
	s_add_i32 m0, s47, 0xc000
	ds_read_b128 v[166:169], v251
	ds_read_b128 v[170:173], v251 offset:1024
	ds_read_b128 v[174:177], v251 offset:2048
	ds_read_b128 v[178:181], v251 offset:3072
	ds_read_b128 v[182:185], v251 offset:4096
	ds_read_b128 v[186:189], v251 offset:5120
	ds_read_b128 v[190:193], v251 offset:6144
	ds_read_b128 v[194:197], v251 offset:7168
	global_load_lds_dwordx4 v[230:231], off
	v_lshl_add_u64 v[230:231], v[228:229], 0, s[10:11]
	s_add_i32 m0, s47, 0xe000
	s_nop 0
	global_load_lds_dwordx4 v[230:231], off
	s_waitcnt vmcnt(8)
	s_waitcnt lgkmcnt(0)
	s_barrier
	s_setprio 1
	s_waitcnt lgkmcnt(0)
	v_mfma_f32_16x16x32_bf16 v[22:25], v[150:153], v[166:169], v[22:25]
	v_mfma_f32_16x16x32_bf16 v[26:29], v[158:161], v[166:169], v[26:29]
	v_mfma_f32_16x16x32_bf16 v[10:13], v[158:161], v[174:177], v[10:13]
	v_mfma_f32_16x16x32_bf16 v[18:21], v[150:153], v[174:177], v[18:21]
	v_mfma_f32_16x16x32_bf16 v[30:33], v[150:153], v[182:185], v[30:33]
	v_mfma_f32_16x16x32_bf16 v[34:37], v[158:161], v[182:185], v[34:37]
	v_mfma_f32_16x16x32_bf16 v[58:61], v[158:161], v[190:193], v[58:61]
	v_mfma_f32_16x16x32_bf16 v[54:57], v[150:153], v[190:193], v[54:57]
	v_mfma_f32_16x16x32_bf16 v[22:25], v[154:157], v[170:173], v[22:25]
	v_mfma_f32_16x16x32_bf16 v[26:29], v[162:165], v[170:173], v[26:29]
	v_mfma_f32_16x16x32_bf16 v[10:13], v[162:165], v[178:181], v[10:13]
	v_mfma_f32_16x16x32_bf16 v[18:21], v[154:157], v[178:181], v[18:21]
	v_mfma_f32_16x16x32_bf16 v[30:33], v[154:157], v[186:189], v[30:33]
	v_mfma_f32_16x16x32_bf16 v[34:37], v[162:165], v[186:189], v[34:37]
	v_mfma_f32_16x16x32_bf16 v[58:61], v[162:165], v[194:197], v[58:61]
	v_mfma_f32_16x16x32_bf16 v[54:57], v[154:157], v[194:197], v[54:57]
	s_setprio 0
	s_setprio 1
	v_mfma_f32_16x16x32_bf16 v[50:53], v[134:137], v[166:169], v[50:53]
	v_mfma_f32_16x16x32_bf16 v[46:49], v[142:145], v[166:169], v[46:49]
	v_mfma_f32_16x16x32_bf16 v[2:5], v[142:145], v[174:177], v[2:5]
	v_mfma_f32_16x16x32_bf16 v[6:9], v[134:137], v[174:177], v[6:9]
	v_mfma_f32_16x16x32_bf16 v[42:45], v[134:137], v[182:185], v[42:45]
	v_mfma_f32_16x16x32_bf16 v[38:41], v[142:145], v[182:185], v[38:41]
	v_mfma_f32_16x16x32_bf16 v[62:65], v[142:145], v[190:193], v[62:65]
	v_mfma_f32_16x16x32_bf16 v[66:69], v[134:137], v[190:193], v[66:69]
	v_mfma_f32_16x16x32_bf16 v[50:53], v[138:141], v[170:173], v[50:53]
	v_mfma_f32_16x16x32_bf16 v[46:49], v[146:149], v[170:173], v[46:49]
	v_mfma_f32_16x16x32_bf16 v[2:5], v[146:149], v[178:181], v[2:5]
	v_mfma_f32_16x16x32_bf16 v[6:9], v[138:141], v[178:181], v[6:9]
	v_mfma_f32_16x16x32_bf16 v[42:45], v[138:141], v[186:189], v[42:45]
	v_mfma_f32_16x16x32_bf16 v[38:41], v[146:149], v[186:189], v[38:41]
	v_mfma_f32_16x16x32_bf16 v[62:65], v[146:149], v[194:197], v[62:65]
	v_mfma_f32_16x16x32_bf16 v[66:69], v[138:141], v[194:197], v[66:69]
	s_setprio 0
	s_barrier
	ds_read_b128 v[190:193], v251 offset:16384
	ds_read_b128 v[194:197], v251 offset:17408
	ds_read_b128 v[182:185], v251 offset:18432
	ds_read_b128 v[186:189], v251 offset:19456
	ds_read_b128 v[174:177], v251 offset:20480
	ds_read_b128 v[178:181], v251 offset:21504
	ds_read_b128 v[166:169], v251 offset:22528
	ds_read_b128 v[170:173], v251 offset:23552
	s_and_b64 s[10:11], s[64:65], s[72:73]
	s_mov_b64 s[72:73], -1
	s_and_b64 vcc, exec, s[10:11]
	v_lshl_add_u64 v[236:237], s[68:69], 0, v[200:201]
	v_lshl_add_u64 v[234:235], s[68:69], 0, v[14:15]
	v_lshl_add_u64 v[232:233], s[70:71], 0, v[202:203]
	v_lshl_add_u64 v[230:231], s[70:71], 0, v[198:199]
	s_cbranch_vccnz .LBB0_1635
	s_mov_b32 m0, s82
	s_add_u32 s72, s68, 0x200000
	global_load_lds_dwordx4 v[236:237], off
	s_mov_b32 m0, s83
	s_addc_u32 s73, s69, 0
	global_load_lds_dwordx4 v[234:235], off
	v_lshl_add_u64 v[240:241], s[72:73], 0, v[200:201]
	s_mov_b32 m0, s84
	s_nop 0
	global_load_lds_dwordx4 v[240:241], off
	v_lshl_add_u64 v[240:241], s[72:73], 0, v[14:15]
	s_mov_b32 m0, s85
	s_mov_b64 s[72:73], 0
	global_load_lds_dwordx4 v[240:241], off
	s_mov_b32 m0, s47
	s_nop 0
	global_load_lds_dwordx4 v[232:233], off
	s_mov_b32 m0, s86
	s_nop 0
	global_load_lds_dwordx4 v[230:231], off
	s_waitcnt vmcnt(8)

.LBB0_1637:
	s_waitcnt lgkmcnt(0)
	s_xor_b64 s[72:73], s[10:11], -1
	s_barrier
	s_setprio 1
	s_waitcnt lgkmcnt(0)
	v_mfma_f32_16x16x32_bf16 v[70:73], v[150:153], v[190:193], v[70:73]
	v_mfma_f32_16x16x32_bf16 v[74:77], v[158:161], v[190:193], v[74:77]
	v_mfma_f32_16x16x32_bf16 v[90:93], v[158:161], v[182:185], v[90:93]
	v_mfma_f32_16x16x32_bf16 v[86:89], v[150:153], v[182:185], v[86:89]
	v_mfma_f32_16x16x32_bf16 v[102:105], v[150:153], v[174:177], v[102:105]
	v_mfma_f32_16x16x32_bf16 v[106:109], v[158:161], v[174:177], v[106:109]
	v_mfma_f32_16x16x32_bf16 v[122:125], v[158:161], v[166:169], v[122:125]
	v_mfma_f32_16x16x32_bf16 v[118:121], v[150:153], v[166:169], v[118:121]
	v_mfma_f32_16x16x32_bf16 v[70:73], v[154:157], v[194:197], v[70:73]
	v_mfma_f32_16x16x32_bf16 v[74:77], v[162:165], v[194:197], v[74:77]
	v_mfma_f32_16x16x32_bf16 v[90:93], v[162:165], v[186:189], v[90:93]
	v_mfma_f32_16x16x32_bf16 v[86:89], v[154:157], v[186:189], v[86:89]
	v_mfma_f32_16x16x32_bf16 v[102:105], v[154:157], v[178:181], v[102:105]
	v_mfma_f32_16x16x32_bf16 v[106:109], v[162:165], v[178:181], v[106:109]
	v_mfma_f32_16x16x32_bf16 v[122:125], v[162:165], v[170:173], v[122:125]
	v_mfma_f32_16x16x32_bf16 v[118:121], v[154:157], v[170:173], v[118:121]
	s_setprio 0
	s_setprio 1
	v_mfma_f32_16x16x32_bf16 v[82:85], v[134:137], v[190:193], v[82:85]
	v_mfma_f32_16x16x32_bf16 v[78:81], v[142:145], v[190:193], v[78:81]
	v_mfma_f32_16x16x32_bf16 v[94:97], v[142:145], v[182:185], v[94:97]
	v_mfma_f32_16x16x32_bf16 v[98:101], v[134:137], v[182:185], v[98:101]
	v_mfma_f32_16x16x32_bf16 v[114:117], v[134:137], v[174:177], v[114:117]
	v_mfma_f32_16x16x32_bf16 v[110:113], v[142:145], v[174:177], v[110:113]
	v_mfma_f32_16x16x32_bf16 v[126:129], v[142:145], v[166:169], v[126:129]
	v_mfma_f32_16x16x32_bf16 v[130:133], v[134:137], v[166:169], v[130:133]
	v_mfma_f32_16x16x32_bf16 v[82:85], v[138:141], v[194:197], v[82:85]
	v_mfma_f32_16x16x32_bf16 v[78:81], v[146:149], v[194:197], v[78:81]
	v_mfma_f32_16x16x32_bf16 v[94:97], v[146:149], v[186:189], v[94:97]
	v_mfma_f32_16x16x32_bf16 v[98:101], v[138:141], v[186:189], v[98:101]
	v_mfma_f32_16x16x32_bf16 v[114:117], v[138:141], v[178:181], v[114:117]
	v_mfma_f32_16x16x32_bf16 v[110:113], v[146:149], v[178:181], v[110:113]
	v_mfma_f32_16x16x32_bf16 v[126:129], v[146:149], v[170:173], v[126:129]
	v_mfma_f32_16x16x32_bf16 v[130:133], v[138:141], v[170:173], v[130:133]
	s_setprio 0
	s_barrier
	v_add_u32_e32 v0, 0x18000, v250
	ds_read_b128 v[150:153], v0
	ds_read_b128 v[154:157], v0 offset:1024
	ds_read_b128 v[158:161], v0 offset:2048
	ds_read_b128 v[162:165], v0 offset:3072
	v_add_u32_e32 v0, 0x1c000, v250
	ds_read_b128 v[134:137], v0
	ds_read_b128 v[138:141], v0 offset:1024
	ds_read_b128 v[142:145], v0 offset:2048
	ds_read_b128 v[146:149], v0 offset:3072
	ds_read_b128 v[190:193], v251 offset:32768
	ds_read_b128 v[194:197], v251 offset:33792
	ds_read_b128 v[182:185], v251 offset:34816
	ds_read_b128 v[186:189], v251 offset:35840
	ds_read_b128 v[174:177], v251 offset:36864
	ds_read_b128 v[178:181], v251 offset:37888
	ds_read_b128 v[166:169], v251 offset:38912
	ds_read_b128 v[170:173], v251 offset:39936
	v_cndmask_b32_e64 v0, 0, 1, s[72:73]
	v_cmp_ne_u32_e64 s[10:11], 1, v0
	s_andn2_b64 vcc, exec, s[72:73]
	s_mov_b64 s[72:73], -1
	s_cbranch_vccnz .LBB0_1639
	s_add_u32 s70, s70, 0x200000
	s_addc_u32 s71, s71, 0
	s_mov_b32 m0, s87
	v_lshl_add_u64 v[240:241], s[70:71], 0, v[202:203]
	global_load_lds_dwordx4 v[240:241], off
	v_lshl_add_u64 v[240:241], s[70:71], 0, v[198:199]
	s_mov_b32 m0, s88
	s_mov_b64 s[72:73], 0
	global_load_lds_dwordx4 v[240:241], off
	s_waitcnt vmcnt(8)

.LBB0_1641:
	s_waitcnt lgkmcnt(0)
	s_barrier
	s_setprio 1
	s_waitcnt lgkmcnt(0)
	v_mfma_f32_16x16x32_bf16 v[22:25], v[150:153], v[190:193], v[22:25]
	v_mfma_f32_16x16x32_bf16 v[26:29], v[158:161], v[190:193], v[26:29]
	v_mfma_f32_16x16x32_bf16 v[10:13], v[158:161], v[182:185], v[10:13]
	v_mfma_f32_16x16x32_bf16 v[18:21], v[150:153], v[182:185], v[18:21]
	v_mfma_f32_16x16x32_bf16 v[30:33], v[150:153], v[174:177], v[30:33]
	v_mfma_f32_16x16x32_bf16 v[34:37], v[158:161], v[174:177], v[34:37]
	v_mfma_f32_16x16x32_bf16 v[58:61], v[158:161], v[166:169], v[58:61]
	v_mfma_f32_16x16x32_bf16 v[54:57], v[150:153], v[166:169], v[54:57]
	v_mfma_f32_16x16x32_bf16 v[22:25], v[154:157], v[194:197], v[22:25]
	v_mfma_f32_16x16x32_bf16 v[26:29], v[162:165], v[194:197], v[26:29]
	v_mfma_f32_16x16x32_bf16 v[10:13], v[162:165], v[186:189], v[10:13]
	v_mfma_f32_16x16x32_bf16 v[18:21], v[154:157], v[186:189], v[18:21]
	v_mfma_f32_16x16x32_bf16 v[30:33], v[154:157], v[178:181], v[30:33]
	v_mfma_f32_16x16x32_bf16 v[34:37], v[162:165], v[178:181], v[34:37]
	v_mfma_f32_16x16x32_bf16 v[58:61], v[162:165], v[170:173], v[58:61]
	v_mfma_f32_16x16x32_bf16 v[54:57], v[154:157], v[170:173], v[54:57]
	s_setprio 0
	s_setprio 1
	v_mfma_f32_16x16x32_bf16 v[50:53], v[134:137], v[190:193], v[50:53]
	v_mfma_f32_16x16x32_bf16 v[46:49], v[142:145], v[190:193], v[46:49]
	v_mfma_f32_16x16x32_bf16 v[2:5], v[142:145], v[182:185], v[2:5]
	v_mfma_f32_16x16x32_bf16 v[6:9], v[134:137], v[182:185], v[6:9]
	v_mfma_f32_16x16x32_bf16 v[42:45], v[134:137], v[174:177], v[42:45]
	v_mfma_f32_16x16x32_bf16 v[38:41], v[142:145], v[174:177], v[38:41]
	v_mfma_f32_16x16x32_bf16 v[62:65], v[142:145], v[166:169], v[62:65]
	v_mfma_f32_16x16x32_bf16 v[66:69], v[134:137], v[166:169], v[66:69]
	v_mfma_f32_16x16x32_bf16 v[50:53], v[138:141], v[194:197], v[50:53]
	v_mfma_f32_16x16x32_bf16 v[46:49], v[146:149], v[194:197], v[46:49]
	v_mfma_f32_16x16x32_bf16 v[2:5], v[146:149], v[186:189], v[2:5]
	v_mfma_f32_16x16x32_bf16 v[6:9], v[138:141], v[186:189], v[6:9]
	v_mfma_f32_16x16x32_bf16 v[42:45], v[138:141], v[178:181], v[42:45]
	v_mfma_f32_16x16x32_bf16 v[38:41], v[146:149], v[178:181], v[38:41]
	v_mfma_f32_16x16x32_bf16 v[62:65], v[146:149], v[170:173], v[62:65]
	v_mfma_f32_16x16x32_bf16 v[66:69], v[138:141], v[170:173], v[66:69]
	s_setprio 0
	s_barrier
	ds_read_b128 v[190:193], v251 offset:49152
	ds_read_b128 v[194:197], v251 offset:50176
	ds_read_b128 v[182:185], v251 offset:51200
	ds_read_b128 v[186:189], v251 offset:52224
	ds_read_b128 v[174:177], v251 offset:53248
	ds_read_b128 v[178:181], v251 offset:54272
	ds_read_b128 v[166:169], v251 offset:55296
	ds_read_b128 v[170:173], v251 offset:56320
	s_and_b64 vcc, exec, s[10:11]
	s_cbranch_vccnz .LBB0_1632
	s_mov_b32 m0, s91
	v_lshl_add_u64 v[236:237], v[236:237], 0, s[16:17]
	s_add_u32 s10, s68, 0x200080
	global_load_lds_dwordx4 v[236:237], off
	v_lshl_add_u64 v[234:235], v[234:235], 0, s[16:17]
	s_mov_b32 m0, s92
	s_addc_u32 s11, s69, 0
	global_load_lds_dwordx4 v[234:235], off
	v_lshl_add_u64 v[234:235], s[10:11], 0, v[200:201]
	s_mov_b32 m0, s3
	v_lshl_add_u64 v[232:233], v[232:233], 0, s[16:17]
	global_load_lds_dwordx4 v[234:235], off
	v_lshl_add_u64 v[234:235], s[10:11], 0, v[14:15]
	s_mov_b32 m0, s95
	v_lshl_add_u64 v[230:231], v[230:231], 0, s[16:17]
	global_load_lds_dwordx4 v[234:235], off
	s_mov_b32 m0, s93
	s_nop 0
	global_load_lds_dwordx4 v[232:233], off
	s_mov_b32 m0, s94
	s_nop 0
	global_load_lds_dwordx4 v[230:231], off
	s_waitcnt vmcnt(8)
	s_branch .LBB0_1632

.LBB0_1717:
	s_waitcnt lgkmcnt(0)
	s_barrier
	s_setprio 1
	s_waitcnt lgkmcnt(0)
	v_mfma_f32_16x16x32_bf16 v[66:69], v[158:161], v[190:193], v[66:69]
	v_mfma_f32_16x16x32_bf16 v[62:65], v[166:169], v[190:193], v[62:65]
	v_mfma_f32_16x16x32_bf16 v[46:49], v[166:169], v[182:185], v[46:49]
	v_mfma_f32_16x16x32_bf16 v[50:53], v[158:161], v[182:185], v[50:53]
	v_mfma_f32_16x16x32_bf16 v[34:37], v[158:161], v[174:177], v[34:37]
	v_mfma_f32_16x16x32_bf16 v[30:33], v[166:169], v[174:177], v[30:33]
	v_mfma_f32_16x16x32_bf16 v[10:13], v[166:169], v[126:129], v[10:13]
	v_mfma_f32_16x16x32_bf16 v[18:21], v[158:161], v[126:129], v[18:21]
	v_mfma_f32_16x16x32_bf16 v[66:69], v[162:165], v[194:197], v[66:69]
	v_mfma_f32_16x16x32_bf16 v[62:65], v[170:173], v[194:197], v[62:65]
	v_mfma_f32_16x16x32_bf16 v[46:49], v[170:173], v[186:189], v[46:49]
	v_mfma_f32_16x16x32_bf16 v[50:53], v[162:165], v[186:189], v[50:53]
	v_mfma_f32_16x16x32_bf16 v[34:37], v[162:165], v[178:181], v[34:37]
	v_mfma_f32_16x16x32_bf16 v[30:33], v[170:173], v[178:181], v[30:33]
	v_mfma_f32_16x16x32_bf16 v[10:13], v[170:173], v[130:133], v[10:13]
	v_mfma_f32_16x16x32_bf16 v[18:21], v[162:165], v[130:133], v[18:21]
	s_setprio 0
	s_setprio 1
	v_mfma_f32_16x16x32_bf16 v[58:61], v[134:137], v[190:193], v[58:61]
	v_mfma_f32_16x16x32_bf16 v[54:57], v[150:153], v[190:193], v[54:57]
	v_mfma_f32_16x16x32_bf16 v[38:41], v[150:153], v[182:185], v[38:41]
	v_mfma_f32_16x16x32_bf16 v[42:45], v[134:137], v[182:185], v[42:45]
	v_mfma_f32_16x16x32_bf16 v[26:29], v[134:137], v[174:177], v[26:29]
	v_mfma_f32_16x16x32_bf16 v[22:25], v[150:153], v[174:177], v[22:25]
	v_mfma_f32_16x16x32_bf16 v[2:5], v[150:153], v[126:129], v[2:5]
	v_mfma_f32_16x16x32_bf16 v[6:9], v[134:137], v[126:129], v[6:9]
	v_mfma_f32_16x16x32_bf16 v[58:61], v[138:141], v[194:197], v[58:61]
	v_mfma_f32_16x16x32_bf16 v[54:57], v[154:157], v[194:197], v[54:57]
	v_mfma_f32_16x16x32_bf16 v[38:41], v[154:157], v[186:189], v[38:41]
	v_mfma_f32_16x16x32_bf16 v[42:45], v[138:141], v[186:189], v[42:45]
	v_mfma_f32_16x16x32_bf16 v[26:29], v[138:141], v[178:181], v[26:29]
	v_mfma_f32_16x16x32_bf16 v[22:25], v[154:157], v[178:181], v[22:25]
	v_mfma_f32_16x16x32_bf16 v[2:5], v[154:157], v[130:133], v[2:5]
	v_mfma_f32_16x16x32_bf16 v[6:9], v[138:141], v[130:133], v[6:9]
	s_setprio 0
	s_barrier
	s_add_i32 s33, s33, 2
	s_add_u32 s50, s50, 0x100
	s_addc_u32 s51, s51, 0
	s_add_u32 s69, s69, 0x100
	s_addc_u32 s70, s70, 0
	s_cmpk_gt_u32 s33, 0x7d
	s_cbranch_scc1 .LBB0_1728
.LBB0_1718:
	v_add_u32_e32 v126, 0x10000, v226
	ds_read_b128 v[158:161], v126
	ds_read_b128 v[162:165], v126 offset:1024
	ds_read_b128 v[166:169], v126 offset:2048
	ds_read_b128 v[170:173], v126 offset:3072
	v_add_u32_e32 v126, 0x14000, v226
	ds_read_b128 v[134:137], v126
	ds_read_b128 v[138:141], v126 offset:1024
	ds_read_b128 v[150:153], v126 offset:2048
	ds_read_b128 v[154:157], v126 offset:3072
	s_add_u32 s54, s50, 0xffe00080
	s_addc_u32 s55, s51, -1
	s_cmpk_lg_i32 s33, 0x7c
	s_cselect_b64 s[56:57], -1, 0
	s_and_b64 s[52:53], s[56:57], exec
	s_cselect_b32 s53, s70, s13
	s_cselect_b32 s52, s69, s68
	s_cselect_b32 s55, s55, s41
	s_cselect_b32 s54, s54, s67
	v_lshl_add_u64 v[126:127], s[50:51], 0, v[212:213]
	s_add_i32 m0, s1, 0xc000
	ds_read_b128 v[174:177], v227
	ds_read_b128 v[178:181], v227 offset:1024
	ds_read_b128 v[182:185], v227 offset:2048
	ds_read_b128 v[186:189], v227 offset:3072
	ds_read_b128 v[190:193], v227 offset:4096
	ds_read_b128 v[194:197], v227 offset:5120
	ds_read_b128 v[198:201], v227 offset:6144
	ds_read_b128 v[202:205], v227 offset:7168
	global_load_lds_dwordx4 v[126:127], off
	v_lshl_add_u64 v[126:127], s[50:51], 0, v[216:217]
	s_add_i32 m0, s1, 0xe000
	s_nop 0
	global_load_lds_dwordx4 v[126:127], off
	s_waitcnt vmcnt(8)
	s_waitcnt lgkmcnt(0)
	s_barrier
	s_setprio 1
	s_waitcnt lgkmcnt(0)
	v_mfma_f32_16x16x32_bf16 v[126:129], v[158:161], v[174:177], v[146:149]
	v_mfma_f32_16x16x32_bf16 v[130:133], v[166:169], v[174:177], v[142:145]
	v_mfma_f32_16x16x32_bf16 v[114:117], v[158:161], v[182:185], v[114:117]
	v_mfma_f32_16x16x32_bf16 v[110:113], v[166:169], v[182:185], v[110:113]
	v_mfma_f32_16x16x32_bf16 v[98:101], v[158:161], v[190:193], v[98:101]
	v_mfma_f32_16x16x32_bf16 v[94:97], v[166:169], v[190:193], v[94:97]
	v_mfma_f32_16x16x32_bf16 v[82:85], v[158:161], v[198:201], v[82:85]
	v_mfma_f32_16x16x32_bf16 v[78:81], v[166:169], v[198:201], v[78:81]
	v_mfma_f32_16x16x32_bf16 v[126:129], v[162:165], v[178:181], v[126:129]
	v_mfma_f32_16x16x32_bf16 v[130:133], v[170:173], v[178:181], v[130:133]
	v_mfma_f32_16x16x32_bf16 v[114:117], v[162:165], v[186:189], v[114:117]
	v_mfma_f32_16x16x32_bf16 v[110:113], v[170:173], v[186:189], v[110:113]
	v_mfma_f32_16x16x32_bf16 v[98:101], v[162:165], v[194:197], v[98:101]
	v_mfma_f32_16x16x32_bf16 v[94:97], v[170:173], v[194:197], v[94:97]
	v_mfma_f32_16x16x32_bf16 v[82:85], v[162:165], v[202:205], v[82:85]
	v_mfma_f32_16x16x32_bf16 v[78:81], v[170:173], v[202:205], v[78:81]
	s_setprio 0
	s_setprio 1
	v_mfma_f32_16x16x32_bf16 v[122:125], v[134:137], v[174:177], v[122:125]
	v_mfma_f32_16x16x32_bf16 v[118:121], v[150:153], v[174:177], v[118:121]
	v_mfma_f32_16x16x32_bf16 v[102:105], v[150:153], v[182:185], v[102:105]
	v_mfma_f32_16x16x32_bf16 v[106:109], v[134:137], v[182:185], v[106:109]
	v_mfma_f32_16x16x32_bf16 v[90:93], v[134:137], v[190:193], v[90:93]
	v_mfma_f32_16x16x32_bf16 v[86:89], v[150:153], v[190:193], v[86:89]
	v_mfma_f32_16x16x32_bf16 v[70:73], v[150:153], v[198:201], v[70:73]
	v_mfma_f32_16x16x32_bf16 v[74:77], v[134:137], v[198:201], v[74:77]
	v_mfma_f32_16x16x32_bf16 v[122:125], v[138:141], v[178:181], v[122:125]
	v_mfma_f32_16x16x32_bf16 v[118:121], v[154:157], v[178:181], v[118:121]
	v_mfma_f32_16x16x32_bf16 v[102:105], v[154:157], v[186:189], v[102:105]
	v_mfma_f32_16x16x32_bf16 v[106:109], v[138:141], v[186:189], v[106:109]
	v_mfma_f32_16x16x32_bf16 v[90:93], v[138:141], v[194:197], v[90:93]
	v_mfma_f32_16x16x32_bf16 v[86:89], v[154:157], v[194:197], v[86:89]
	v_mfma_f32_16x16x32_bf16 v[70:73], v[154:157], v[202:205], v[70:73]
	v_mfma_f32_16x16x32_bf16 v[74:77], v[138:141], v[202:205], v[74:77]
	s_setprio 0
	s_barrier
	ds_read_b128 v[190:193], v227 offset:16384
	ds_read_b128 v[194:197], v227 offset:17408
	ds_read_b128 v[182:185], v227 offset:18432
	ds_read_b128 v[186:189], v227 offset:19456
	ds_read_b128 v[174:177], v227 offset:20480
	ds_read_b128 v[178:181], v227 offset:21504
	ds_read_b128 v[142:145], v227 offset:22528
	ds_read_b128 v[146:149], v227 offset:23552
	s_or_b64 s[56:57], s[42:43], s[56:57]
	s_xor_b64 s[58:59], s[56:57], -1
	s_mov_b64 s[60:61], -1
	s_and_b64 vcc, exec, s[58:59]
	s_cbranch_vccz .LBB0_1720
	s_waitcnt vmcnt(2)
	s_mov_b64 s[60:61], 0

.LBB0_1722:
	s_waitcnt lgkmcnt(0)
	s_barrier
	s_setprio 1
	s_waitcnt lgkmcnt(0)
	v_mfma_f32_16x16x32_bf16 v[66:69], v[158:161], v[190:193], v[66:69]
	v_mfma_f32_16x16x32_bf16 v[62:65], v[166:169], v[190:193], v[62:65]
	v_mfma_f32_16x16x32_bf16 v[46:49], v[166:169], v[182:185], v[46:49]
	v_mfma_f32_16x16x32_bf16 v[50:53], v[158:161], v[182:185], v[50:53]
	v_mfma_f32_16x16x32_bf16 v[34:37], v[158:161], v[174:177], v[34:37]
	v_mfma_f32_16x16x32_bf16 v[30:33], v[166:169], v[174:177], v[30:33]
	v_mfma_f32_16x16x32_bf16 v[10:13], v[166:169], v[142:145], v[10:13]
	v_mfma_f32_16x16x32_bf16 v[18:21], v[158:161], v[142:145], v[18:21]
	v_mfma_f32_16x16x32_bf16 v[66:69], v[162:165], v[194:197], v[66:69]
	v_mfma_f32_16x16x32_bf16 v[62:65], v[170:173], v[194:197], v[62:65]
	v_mfma_f32_16x16x32_bf16 v[46:49], v[170:173], v[186:189], v[46:49]
	v_mfma_f32_16x16x32_bf16 v[50:53], v[162:165], v[186:189], v[50:53]
	v_mfma_f32_16x16x32_bf16 v[34:37], v[162:165], v[178:181], v[34:37]
	v_mfma_f32_16x16x32_bf16 v[30:33], v[170:173], v[178:181], v[30:33]
	v_mfma_f32_16x16x32_bf16 v[10:13], v[170:173], v[146:149], v[10:13]
	v_mfma_f32_16x16x32_bf16 v[18:21], v[162:165], v[146:149], v[18:21]
	s_setprio 0
	s_setprio 1
	v_mfma_f32_16x16x32_bf16 v[58:61], v[134:137], v[190:193], v[58:61]
	v_mfma_f32_16x16x32_bf16 v[54:57], v[150:153], v[190:193], v[54:57]
	v_mfma_f32_16x16x32_bf16 v[38:41], v[150:153], v[182:185], v[38:41]
	v_mfma_f32_16x16x32_bf16 v[42:45], v[134:137], v[182:185], v[42:45]
	v_mfma_f32_16x16x32_bf16 v[26:29], v[134:137], v[174:177], v[26:29]
	v_mfma_f32_16x16x32_bf16 v[22:25], v[150:153], v[174:177], v[22:25]
	v_mfma_f32_16x16x32_bf16 v[2:5], v[150:153], v[142:145], v[2:5]
	v_mfma_f32_16x16x32_bf16 v[6:9], v[134:137], v[142:145], v[6:9]
	v_mfma_f32_16x16x32_bf16 v[58:61], v[138:141], v[194:197], v[58:61]
	v_mfma_f32_16x16x32_bf16 v[54:57], v[154:157], v[194:197], v[54:57]
	v_mfma_f32_16x16x32_bf16 v[38:41], v[154:157], v[186:189], v[38:41]
	v_mfma_f32_16x16x32_bf16 v[42:45], v[138:141], v[186:189], v[42:45]
	v_mfma_f32_16x16x32_bf16 v[26:29], v[138:141], v[178:181], v[26:29]
	v_mfma_f32_16x16x32_bf16 v[22:25], v[154:157], v[178:181], v[22:25]
	v_mfma_f32_16x16x32_bf16 v[2:5], v[154:157], v[146:149], v[2:5]
	v_mfma_f32_16x16x32_bf16 v[6:9], v[138:141], v[146:149], v[6:9]
	s_setprio 0
	s_barrier
	v_add_u32_e32 v134, 0x18000, v226
	v_add_u32_e32 v142, 0x1c000, v226
	ds_read_b128 v[158:161], v134
	ds_read_b128 v[162:165], v134 offset:1024
	ds_read_b128 v[166:169], v134 offset:2048
	ds_read_b128 v[170:173], v134 offset:3072
	ds_read_b128 v[134:137], v142
	ds_read_b128 v[138:141], v142 offset:1024
	ds_read_b128 v[150:153], v142 offset:2048
	ds_read_b128 v[154:157], v142 offset:3072
	ds_read_b128 v[198:201], v227 offset:32768
	ds_read_b128 v[202:205], v227 offset:33792
	ds_read_b128 v[190:193], v227 offset:34816
	ds_read_b128 v[194:197], v227 offset:35840
	ds_read_b128 v[182:185], v227 offset:36864
	ds_read_b128 v[186:189], v227 offset:37888
	ds_read_b128 v[174:177], v227 offset:38912
	ds_read_b128 v[178:181], v227 offset:39936
	s_mov_b64 s[60:61], -1
	s_and_b64 vcc, exec, s[58:59]
	s_cbranch_vccz .LBB0_1724
	s_waitcnt vmcnt(0)
	s_mov_b64 s[60:61], 0

.LBB0_1726:
	s_waitcnt lgkmcnt(0)
	s_barrier
	s_setprio 1
	s_waitcnt lgkmcnt(0)
	v_mfma_f32_16x16x32_bf16 v[126:129], v[158:161], v[198:201], v[126:129]
	v_mfma_f32_16x16x32_bf16 v[146:149], v[162:165], v[202:205], v[126:129]
	v_mfma_f32_16x16x32_bf16 v[126:129], v[166:169], v[198:201], v[130:133]
	v_mfma_f32_16x16x32_bf16 v[114:117], v[158:161], v[190:193], v[114:117]
	v_mfma_f32_16x16x32_bf16 v[110:113], v[166:169], v[190:193], v[110:113]
	v_mfma_f32_16x16x32_bf16 v[98:101], v[158:161], v[182:185], v[98:101]
	v_mfma_f32_16x16x32_bf16 v[94:97], v[166:169], v[182:185], v[94:97]
	v_mfma_f32_16x16x32_bf16 v[82:85], v[158:161], v[174:177], v[82:85]
	v_mfma_f32_16x16x32_bf16 v[78:81], v[166:169], v[174:177], v[78:81]
	v_mfma_f32_16x16x32_bf16 v[142:145], v[170:173], v[202:205], v[126:129]
	v_mfma_f32_16x16x32_bf16 v[114:117], v[162:165], v[194:197], v[114:117]
	v_mfma_f32_16x16x32_bf16 v[110:113], v[170:173], v[194:197], v[110:113]
	v_mfma_f32_16x16x32_bf16 v[98:101], v[162:165], v[186:189], v[98:101]
	v_mfma_f32_16x16x32_bf16 v[94:97], v[170:173], v[186:189], v[94:97]
	v_mfma_f32_16x16x32_bf16 v[82:85], v[162:165], v[178:181], v[82:85]
	v_mfma_f32_16x16x32_bf16 v[78:81], v[170:173], v[178:181], v[78:81]
	s_setprio 0
	s_setprio 1
	v_mfma_f32_16x16x32_bf16 v[122:125], v[134:137], v[198:201], v[122:125]
	v_mfma_f32_16x16x32_bf16 v[118:121], v[150:153], v[198:201], v[118:121]
	v_mfma_f32_16x16x32_bf16 v[102:105], v[150:153], v[190:193], v[102:105]
	v_mfma_f32_16x16x32_bf16 v[106:109], v[134:137], v[190:193], v[106:109]
	v_mfma_f32_16x16x32_bf16 v[90:93], v[134:137], v[182:185], v[90:93]
	v_mfma_f32_16x16x32_bf16 v[86:89], v[150:153], v[182:185], v[86:89]
	v_mfma_f32_16x16x32_bf16 v[70:73], v[150:153], v[174:177], v[70:73]
	v_mfma_f32_16x16x32_bf16 v[74:77], v[134:137], v[174:177], v[74:77]
	v_mfma_f32_16x16x32_bf16 v[122:125], v[138:141], v[202:205], v[122:125]
	v_mfma_f32_16x16x32_bf16 v[118:121], v[154:157], v[202:205], v[118:121]
	v_mfma_f32_16x16x32_bf16 v[102:105], v[154:157], v[194:197], v[102:105]
	v_mfma_f32_16x16x32_bf16 v[106:109], v[138:141], v[194:197], v[106:109]
	v_mfma_f32_16x16x32_bf16 v[90:93], v[138:141], v[186:189], v[90:93]
	v_mfma_f32_16x16x32_bf16 v[86:89], v[154:157], v[186:189], v[86:89]
	v_mfma_f32_16x16x32_bf16 v[70:73], v[154:157], v[178:181], v[70:73]
	v_mfma_f32_16x16x32_bf16 v[74:77], v[138:141], v[178:181], v[74:77]
	s_setprio 0
	s_barrier
	ds_read_b128 v[190:193], v227 offset:49152
	ds_read_b128 v[194:197], v227 offset:50176
	ds_read_b128 v[182:185], v227 offset:51200
	ds_read_b128 v[186:189], v227 offset:52224
	ds_read_b128 v[174:177], v227 offset:53248
	ds_read_b128 v[178:181], v227 offset:54272
	ds_read_b128 v[126:129], v227 offset:55296
	ds_read_b128 v[130:133], v227 offset:56320
	s_andn2_b64 vcc, exec, s[56:57]
	s_cbranch_vccnz .LBB0_1717
	s_mov_b32 m0, s29
	v_lshl_add_u64 v[198:199], v[224:225], 0, s[16:17]
	s_add_u32 s52, s52, 0x200080
	global_load_lds_dwordx4 v[198:199], off
	v_lshl_add_u64 v[198:199], v[222:223], 0, s[16:17]
	s_mov_b32 m0, s36
	s_addc_u32 s53, s53, 0
	global_load_lds_dwordx4 v[198:199], off
	v_lshl_add_u64 v[198:199], s[52:53], 0, v[206:207]
	s_mov_b32 m0, s62
	s_nop 0
	global_load_lds_dwordx4 v[198:199], off
	v_lshl_add_u64 v[198:199], s[52:53], 0, v[210:211]
	s_mov_b32 m0, s63
	s_nop 0
	global_load_lds_dwordx4 v[198:199], off
	v_lshl_add_u64 v[198:199], v[220:221], 0, s[16:17]
	s_mov_b32 m0, s38
	s_nop 0
	global_load_lds_dwordx4 v[198:199], off
	v_lshl_add_u64 v[198:199], v[218:219], 0, s[16:17]
	s_mov_b32 m0, s49
	s_nop 0
	global_load_lds_dwordx4 v[198:199], off
	s_waitcnt vmcnt(8)
	s_branch .LBB0_1717
